# priority flips plus exact counted lgkmcnt waits in the attention MFMA blocks
# speedup vs baseline: 1.0088x; 1.0031x over previous
.LBB0_599:
	s_setprio 3
	s_mov_b32 s75, s74
	s_mov_b32 s74, s0
	v_add_u32_e32 v238, s74, v193
	ds_read_b128 v[82:85], v188 offset:40960
	ds_read_b128 v[210:213], v188 offset:45056
	ds_read_b128 v[214:217], v189 offset:40960
	ds_read_b128 v[218:221], v189 offset:45056
	ds_read_b128 v[222:225], v190 offset:40960
	ds_read_b128 v[226:229], v190 offset:45056
	ds_read_b128 v[230:233], v191 offset:40960
	ds_read_b128 v[234:237], v191 offset:45056
	ds_read_b64_tr_b16 v[194:195], v238 offset:0
	ds_read_b64_tr_b16 v[196:197], v238 offset:0x800
	ds_read_b64_tr_b16 v[198:199], v238 offset:0x1000
	ds_read_b64_tr_b16 v[200:201], v238 offset:0x1800
	s_waitcnt lgkmcnt(11)
	v_mfma_f32_32x32x16_bf16 v[98:113], v[82:85], v[126:129], v[66:81]
	s_waitcnt lgkmcnt(10)
	v_mfma_f32_32x32x16_bf16 v[82:97], v[210:213], v[126:129], v[66:81]
	ds_read_b64_tr_b16 v[202:203], v238 offset:0x2000
	ds_read_b64_tr_b16 v[204:205], v238 offset:0x2800
	ds_read_b64_tr_b16 v[206:207], v238 offset:0x3000
	ds_read_b64_tr_b16 v[208:209], v238 offset:0x3800
	s_waitcnt lgkmcnt(13)
	v_mfma_f32_32x32x16_bf16 v[98:113], v[214:217], v[122:125], v[98:113]
	s_waitcnt lgkmcnt(12)
	v_mfma_f32_32x32x16_bf16 v[82:97], v[218:221], v[122:125], v[82:97]
	s_waitcnt lgkmcnt(11)
	v_mfma_f32_32x32x16_bf16 v[98:113], v[222:225], v[118:121], v[98:113]
	s_waitcnt lgkmcnt(10)
	v_mfma_f32_32x32x16_bf16 v[82:97], v[226:229], v[118:121], v[82:97]
	s_waitcnt lgkmcnt(9)
	v_mfma_f32_32x32x16_bf16 v[98:113], v[230:233], v[114:117], v[98:113]
	s_waitcnt lgkmcnt(8)
	v_mfma_f32_32x32x16_bf16 v[82:97], v[234:237], v[114:117], v[82:97]
	ds_read_b64_tr_b16 v[210:211], v238 offset:0x200
	ds_read_b64_tr_b16 v[212:213], v238 offset:0xa00
	ds_read_b64_tr_b16 v[214:215], v238 offset:0x1200
	ds_read_b64_tr_b16 v[216:217], v238 offset:0x1a00
	ds_read_b64_tr_b16 v[218:219], v238 offset:0x2200
	ds_read_b64_tr_b16 v[220:221], v238 offset:0x2a00
	ds_read_b64_tr_b16 v[222:223], v238 offset:0x3200
	ds_read_b64_tr_b16 v[224:225], v238 offset:0x3a00
	s_waitcnt lgkmcnt(14)
	v_mfma_f32_32x32x16_bf16 v[50:65], v[142:145], v[194:197], v[50:65]
	s_waitcnt lgkmcnt(12)
	v_mfma_f32_32x32x16_bf16 v[50:65], v[138:141], v[198:201], v[50:65]
	s_waitcnt lgkmcnt(10)
	v_mfma_f32_32x32x16_bf16 v[50:65], v[134:137], v[202:205], v[50:65]
	s_waitcnt lgkmcnt(8)
	v_mfma_f32_32x32x16_bf16 v[50:65], v[130:133], v[206:209], v[50:65]
	ds_read_b64_tr_b16 v[194:195], v238 offset:0x400
	ds_read_b64_tr_b16 v[196:197], v238 offset:0xc00
	ds_read_b64_tr_b16 v[198:199], v238 offset:0x1400
	ds_read_b64_tr_b16 v[200:201], v238 offset:0x1c00
	ds_read_b64_tr_b16 v[202:203], v238 offset:0x2400
	ds_read_b64_tr_b16 v[204:205], v238 offset:0x2c00
	ds_read_b64_tr_b16 v[206:207], v238 offset:0x3400
	ds_read_b64_tr_b16 v[208:209], v238 offset:0x3c00
	s_waitcnt lgkmcnt(14)
	v_mfma_f32_32x32x16_bf16 v[34:49], v[142:145], v[210:213], v[34:49]
	s_waitcnt lgkmcnt(12)
	v_mfma_f32_32x32x16_bf16 v[34:49], v[138:141], v[214:217], v[34:49]
	s_waitcnt lgkmcnt(10)
	v_mfma_f32_32x32x16_bf16 v[34:49], v[134:137], v[218:221], v[34:49]
	s_waitcnt lgkmcnt(8)
	v_mfma_f32_32x32x16_bf16 v[34:49], v[130:133], v[222:225], v[34:49]
	ds_read_b64_tr_b16 v[210:211], v238 offset:0x600
	ds_read_b64_tr_b16 v[212:213], v238 offset:0xe00
	ds_read_b64_tr_b16 v[214:215], v238 offset:0x1600
	ds_read_b64_tr_b16 v[216:217], v238 offset:0x1e00
	ds_read_b64_tr_b16 v[218:219], v238 offset:0x2600
	ds_read_b64_tr_b16 v[220:221], v238 offset:0x2e00
	ds_read_b64_tr_b16 v[222:223], v238 offset:0x3600
	ds_read_b64_tr_b16 v[224:225], v238 offset:0x3e00
	s_waitcnt lgkmcnt(14)
	v_mfma_f32_32x32x16_bf16 v[18:33], v[142:145], v[194:197], v[18:33]
	s_waitcnt lgkmcnt(12)
	v_mfma_f32_32x32x16_bf16 v[18:33], v[138:141], v[198:201], v[18:33]
	s_waitcnt lgkmcnt(10)
	v_mfma_f32_32x32x16_bf16 v[18:33], v[134:137], v[202:205], v[18:33]
	s_waitcnt lgkmcnt(8)
	v_mfma_f32_32x32x16_bf16 v[18:33], v[130:133], v[206:209], v[18:33]
	s_waitcnt lgkmcnt(6)
	v_mfma_f32_32x32x16_bf16 v[2:17], v[142:145], v[210:213], v[2:17]
	s_waitcnt lgkmcnt(4)
	v_mfma_f32_32x32x16_bf16 v[2:17], v[138:141], v[214:217], v[2:17]
	s_waitcnt lgkmcnt(2)
	v_mfma_f32_32x32x16_bf16 v[2:17], v[134:137], v[218:221], v[2:17]
	s_waitcnt lgkmcnt(0)
	v_mfma_f32_32x32x16_bf16 v[2:17], v[130:133], v[222:225], v[2:17]
	s_and_b64 vcc, exec, s[6:7]
	s_cbranch_vccnz .LBB0_601
	s_waitcnt vmcnt(1)

.LBB0_612:
	s_barrier
	s_setprio 3
	v_add_u32_e32 v197, s75, v193
	ds_read_b128 v[82:85], v188 offset:32768
	ds_read_b128 v[214:217], v188 offset:36864
	ds_read_b128 v[218:221], v189 offset:32768
	ds_read_b128 v[222:225], v189 offset:36864
	ds_read_b128 v[226:229], v190 offset:32768
	ds_read_b128 v[230:233], v190 offset:36864
	ds_read_b128 v[234:237], v191 offset:32768
	ds_read_b128 v[238:241], v191 offset:36864
	ds_read_b64_tr_b16 v[198:199], v197 offset:0
	ds_read_b64_tr_b16 v[200:201], v197 offset:0x800
	ds_read_b64_tr_b16 v[202:203], v197 offset:0x1000
	ds_read_b64_tr_b16 v[204:205], v197 offset:0x1800
	s_waitcnt lgkmcnt(11)
	v_mfma_f32_32x32x16_bf16 v[98:113], v[82:85], v[126:129], v[66:81]
	s_waitcnt lgkmcnt(10)
	v_mfma_f32_32x32x16_bf16 v[82:97], v[214:217], v[126:129], v[66:81]
	ds_read_b64_tr_b16 v[206:207], v197 offset:0x2000
	ds_read_b64_tr_b16 v[208:209], v197 offset:0x2800
	ds_read_b64_tr_b16 v[210:211], v197 offset:0x3000
	ds_read_b64_tr_b16 v[212:213], v197 offset:0x3800
	s_waitcnt lgkmcnt(13)
	v_mfma_f32_32x32x16_bf16 v[98:113], v[218:221], v[122:125], v[98:113]
	s_waitcnt lgkmcnt(12)
	v_mfma_f32_32x32x16_bf16 v[82:97], v[222:225], v[122:125], v[82:97]
	s_waitcnt lgkmcnt(11)
	v_mfma_f32_32x32x16_bf16 v[98:113], v[226:229], v[118:121], v[98:113]
	s_waitcnt lgkmcnt(10)
	v_mfma_f32_32x32x16_bf16 v[82:97], v[230:233], v[118:121], v[82:97]
	s_waitcnt lgkmcnt(9)
	v_mfma_f32_32x32x16_bf16 v[98:113], v[234:237], v[114:117], v[98:113]
	s_waitcnt lgkmcnt(8)
	v_mfma_f32_32x32x16_bf16 v[82:97], v[238:241], v[114:117], v[82:97]
	ds_read_b64_tr_b16 v[214:215], v197 offset:0x200
	ds_read_b64_tr_b16 v[216:217], v197 offset:0xa00
	ds_read_b64_tr_b16 v[218:219], v197 offset:0x1200
	ds_read_b64_tr_b16 v[220:221], v197 offset:0x1a00
	ds_read_b64_tr_b16 v[222:223], v197 offset:0x2200
	ds_read_b64_tr_b16 v[224:225], v197 offset:0x2a00
	ds_read_b64_tr_b16 v[226:227], v197 offset:0x3200
	ds_read_b64_tr_b16 v[228:229], v197 offset:0x3a00
	s_waitcnt lgkmcnt(14)
	v_mfma_f32_32x32x16_bf16 v[50:65], v[142:145], v[198:201], v[50:65]
	s_waitcnt lgkmcnt(12)
	v_mfma_f32_32x32x16_bf16 v[50:65], v[138:141], v[202:205], v[50:65]
	s_waitcnt lgkmcnt(10)
	v_mfma_f32_32x32x16_bf16 v[50:65], v[134:137], v[206:209], v[50:65]
	s_waitcnt lgkmcnt(8)
	v_mfma_f32_32x32x16_bf16 v[50:65], v[130:133], v[210:213], v[50:65]
	ds_read_b64_tr_b16 v[198:199], v197 offset:0x400
	ds_read_b64_tr_b16 v[200:201], v197 offset:0xc00
	ds_read_b64_tr_b16 v[202:203], v197 offset:0x1400
	ds_read_b64_tr_b16 v[204:205], v197 offset:0x1c00
	ds_read_b64_tr_b16 v[206:207], v197 offset:0x2400
	ds_read_b64_tr_b16 v[208:209], v197 offset:0x2c00
	ds_read_b64_tr_b16 v[210:211], v197 offset:0x3400
	ds_read_b64_tr_b16 v[212:213], v197 offset:0x3c00
	s_waitcnt lgkmcnt(14)
	v_mfma_f32_32x32x16_bf16 v[34:49], v[142:145], v[214:217], v[34:49]
	s_waitcnt lgkmcnt(12)
	v_mfma_f32_32x32x16_bf16 v[34:49], v[138:141], v[218:221], v[34:49]
	s_waitcnt lgkmcnt(10)
	v_mfma_f32_32x32x16_bf16 v[34:49], v[134:137], v[222:225], v[34:49]
	s_waitcnt lgkmcnt(8)
	v_mfma_f32_32x32x16_bf16 v[34:49], v[130:133], v[226:229], v[34:49]
	ds_read_b64_tr_b16 v[214:215], v197 offset:0x600
	ds_read_b64_tr_b16 v[216:217], v197 offset:0xe00
	ds_read_b64_tr_b16 v[218:219], v197 offset:0x1600
	ds_read_b64_tr_b16 v[220:221], v197 offset:0x1e00
	ds_read_b64_tr_b16 v[222:223], v197 offset:0x2600
	ds_read_b64_tr_b16 v[224:225], v197 offset:0x2e00
	ds_read_b64_tr_b16 v[226:227], v197 offset:0x3600
	ds_read_b64_tr_b16 v[228:229], v197 offset:0x3e00
	s_waitcnt lgkmcnt(14)
	v_mfma_f32_32x32x16_bf16 v[18:33], v[142:145], v[198:201], v[18:33]
	s_waitcnt lgkmcnt(12)
	v_mfma_f32_32x32x16_bf16 v[18:33], v[138:141], v[202:205], v[18:33]
	s_waitcnt lgkmcnt(10)
	v_mfma_f32_32x32x16_bf16 v[18:33], v[134:137], v[206:209], v[18:33]
	s_waitcnt lgkmcnt(8)
	v_mfma_f32_32x32x16_bf16 v[18:33], v[130:133], v[210:213], v[18:33]
	s_waitcnt lgkmcnt(6)
	v_mfma_f32_32x32x16_bf16 v[2:17], v[142:145], v[214:217], v[2:17]
	s_waitcnt lgkmcnt(4)
	v_mfma_f32_32x32x16_bf16 v[2:17], v[138:141], v[218:221], v[2:17]
	s_waitcnt lgkmcnt(2)
	v_mfma_f32_32x32x16_bf16 v[2:17], v[134:137], v[222:225], v[2:17]
	s_waitcnt lgkmcnt(0)
	v_mfma_f32_32x32x16_bf16 v[2:17], v[130:133], v[226:229], v[2:17]
	s_and_b64 vcc, exec, s[6:7]
	s_cbranch_vccnz .LBB0_614
	s_waitcnt vmcnt(1)

.LBB0_666:
	s_setprio 3
	v_add_u32_e32 v189, v187, v160
	v_add_u32_e32 v190, v187, v162
	v_add_u32_e32 v191, v187, v164
	v_add_u32_e32 v192, v187, v166
	ds_read_b128 v[66:69], v189 offset:16384
	ds_read_b128 v[70:73], v189 offset:24576
	ds_read_b128 v[194:197], v190 offset:16384
	ds_read_b128 v[198:201], v190 offset:24576
	ds_read_b128 v[202:205], v191 offset:16384
	ds_read_b128 v[206:209], v191 offset:24576
	ds_read_b128 v[210:213], v192 offset:16384
	ds_read_b128 v[214:217], v192 offset:24576
	s_mov_b32 s12, s94
	s_mov_b32 s94, s8
	v_add_u32_e32 v250, s94, v185
	s_waitcnt lgkmcnt(7)
	v_mfma_f32_32x32x16_bf16 v[82:97], v[66:69], v[114:117], 0
	s_waitcnt lgkmcnt(6)
	v_mfma_f32_32x32x16_bf16 v[66:81], v[70:73], v[114:117], 0
	s_waitcnt lgkmcnt(5)
	v_mfma_f32_32x32x16_bf16 v[82:97], v[194:197], v[110:113], v[82:97]
	s_waitcnt lgkmcnt(4)
	v_mfma_f32_32x32x16_bf16 v[66:81], v[198:201], v[110:113], v[66:81]
	v_add_u32_e32 v193, v187, v168
	v_add_u32_e32 v194, v187, v170
	ds_read_b128 v[198:201], v193 offset:24576
	ds_read_b128 v[218:221], v194 offset:16384
	ds_read_b128 v[222:225], v194 offset:24576
	ds_read_b128 v[226:229], v193 offset:16384
	ds_read_b128 v[230:233], v159
	s_waitcnt lgkmcnt(8)
	v_mfma_f32_32x32x16_bf16 v[82:97], v[202:205], v[106:109], v[82:97]
	s_waitcnt lgkmcnt(7)
	v_mfma_f32_32x32x16_bf16 v[66:81], v[206:209], v[106:109], v[66:81]
	s_waitcnt lgkmcnt(6)
	v_mfma_f32_32x32x16_bf16 v[82:97], v[210:213], v[102:105], v[82:97]
	s_waitcnt lgkmcnt(5)
	v_mfma_f32_32x32x16_bf16 v[66:81], v[214:217], v[102:105], v[66:81]
	v_add_u32_e32 v195, v187, v172
	v_add_u32_e32 v196, v187, v174
	ds_read_b128 v[202:205], v195 offset:16384
	ds_read_b128 v[206:209], v195 offset:24576
	ds_read_b128 v[210:213], v196 offset:16384
	ds_read_b128 v[214:217], v196 offset:24576
	ds_read_b128 v[234:237], v159 offset:1024
	ds_read_b128 v[238:241], v159 offset:2048
	s_waitcnt lgkmcnt(7)
	v_mfma_f32_32x32x16_bf16 v[82:97], v[226:229], v[98:101], v[82:97]
	v_mfma_f32_32x32x16_bf16 v[66:81], v[198:201], v[98:101], v[66:81]
	s_waitcnt lgkmcnt(6)
	v_mfma_f32_32x32x16_bf16 v[82:97], v[218:221], v[230:233], v[82:97]
	v_mfma_f32_32x32x16_bf16 v[66:81], v[222:225], v[230:233], v[66:81]
	v_add_u32_e32 v197, v188, v177
	v_add_u32_e32 v198, v188, v179
	ds_read_b128 v[218:221], v197 offset:40960
	ds_read_b128 v[222:225], v197 offset:45056
	ds_read_b128 v[226:229], v198 offset:40960
	ds_read_b128 v[230:233], v198 offset:45056
	ds_read_b128 v[242:245], v159 offset:3072
	ds_read_b128 v[246:249], v159 offset:4096
	s_waitcnt lgkmcnt(7)
	v_mfma_f32_32x32x16_bf16 v[82:97], v[202:205], v[234:237], v[82:97]
	v_mfma_f32_32x32x16_bf16 v[66:81], v[206:209], v[234:237], v[66:81]
	s_waitcnt lgkmcnt(6)
	v_mfma_f32_32x32x16_bf16 v[82:97], v[210:213], v[238:241], v[82:97]
	v_mfma_f32_32x32x16_bf16 v[66:81], v[214:217], v[238:241], v[66:81]
	v_add_u32_e32 v199, v188, v181
	v_add_u32_e32 v200, v188, v183
	ds_read_b128 v[202:205], v199 offset:40960
	ds_read_b128 v[206:209], v199 offset:45056
	ds_read_b128 v[210:213], v200 offset:40960
	ds_read_b128 v[214:217], v200 offset:45056
	ds_read_b128 v[234:237], v159 offset:5120
	ds_read_b128 v[238:241], v159 offset:6144
	s_waitcnt lgkmcnt(7)
	v_mfma_f32_32x32x16_bf16 v[82:97], v[218:221], v[242:245], v[82:97]
	v_mfma_f32_32x32x16_bf16 v[66:81], v[222:225], v[242:245], v[66:81]
	s_waitcnt lgkmcnt(6)
	v_mfma_f32_32x32x16_bf16 v[82:97], v[226:229], v[246:249], v[82:97]
	v_mfma_f32_32x32x16_bf16 v[66:81], v[230:233], v[246:249], v[66:81]
	s_waitcnt lgkmcnt(1)
	v_mfma_f32_32x32x16_bf16 v[82:97], v[202:205], v[234:237], v[82:97]
	v_mfma_f32_32x32x16_bf16 v[66:81], v[206:209], v[234:237], v[66:81]
	s_waitcnt lgkmcnt(0)
	v_mfma_f32_32x32x16_bf16 v[82:97], v[210:213], v[238:241], v[82:97]
	v_mfma_f32_32x32x16_bf16 v[66:81], v[214:217], v[238:241], v[66:81]
	ds_read_b64_tr_b16 v[202:203], v250 offset:0
	ds_read_b64_tr_b16 v[204:205], v250 offset:0x800
	ds_read_b64_tr_b16 v[206:207], v250 offset:0x1000
	ds_read_b64_tr_b16 v[208:209], v250 offset:0x1800
	ds_read_b64_tr_b16 v[210:211], v250 offset:0x2000
	ds_read_b64_tr_b16 v[212:213], v250 offset:0x2800
	ds_read_b64_tr_b16 v[214:215], v250 offset:0x3000
	ds_read_b64_tr_b16 v[216:217], v250 offset:0x3800
	ds_read_b64_tr_b16 v[218:219], v250 offset:0x200
	ds_read_b64_tr_b16 v[220:221], v250 offset:0xa00
	ds_read_b64_tr_b16 v[222:223], v250 offset:0x1200
	ds_read_b64_tr_b16 v[224:225], v250 offset:0x1a00
	ds_read_b64_tr_b16 v[226:227], v250 offset:0x2200
	ds_read_b64_tr_b16 v[228:229], v250 offset:0x2a00
	ds_read_b64_tr_b16 v[230:231], v250 offset:0x3200
	ds_read_b64_tr_b16 v[232:233], v250 offset:0x3a00
	s_nop 0
	s_waitcnt lgkmcnt(14)
	v_mfma_f32_32x32x16_bf16 v[50:65], v[130:133], v[202:205], v[50:65]
	s_waitcnt lgkmcnt(12)
	v_mfma_f32_32x32x16_bf16 v[50:65], v[126:129], v[206:209], v[50:65]
	s_waitcnt lgkmcnt(10)
	v_mfma_f32_32x32x16_bf16 v[50:65], v[122:125], v[210:213], v[50:65]
	s_waitcnt lgkmcnt(8)
	v_mfma_f32_32x32x16_bf16 v[50:65], v[118:121], v[214:217], v[50:65]
	ds_read_b64_tr_b16 v[202:203], v250 offset:0x400
	ds_read_b64_tr_b16 v[204:205], v250 offset:0xc00
	ds_read_b64_tr_b16 v[206:207], v250 offset:0x1400
	ds_read_b64_tr_b16 v[208:209], v250 offset:0x1c00
	ds_read_b64_tr_b16 v[210:211], v250 offset:0x2400
	ds_read_b64_tr_b16 v[212:213], v250 offset:0x2c00
	ds_read_b64_tr_b16 v[214:215], v250 offset:0x3400
	ds_read_b64_tr_b16 v[216:217], v250 offset:0x3c00
	s_waitcnt lgkmcnt(14)
	v_mfma_f32_32x32x16_bf16 v[34:49], v[130:133], v[218:221], v[34:49]
	s_waitcnt lgkmcnt(12)
	v_mfma_f32_32x32x16_bf16 v[34:49], v[126:129], v[222:225], v[34:49]
	s_waitcnt lgkmcnt(10)
	v_mfma_f32_32x32x16_bf16 v[34:49], v[122:125], v[226:229], v[34:49]
	s_waitcnt lgkmcnt(8)
	v_mfma_f32_32x32x16_bf16 v[34:49], v[118:121], v[230:233], v[34:49]
	ds_read_b64_tr_b16 v[218:219], v250 offset:0x600
	ds_read_b64_tr_b16 v[220:221], v250 offset:0xe00
	ds_read_b64_tr_b16 v[222:223], v250 offset:0x1600
	ds_read_b64_tr_b16 v[224:225], v250 offset:0x1e00
	ds_read_b64_tr_b16 v[226:227], v250 offset:0x2600
	ds_read_b64_tr_b16 v[228:229], v250 offset:0x2e00
	ds_read_b64_tr_b16 v[230:231], v250 offset:0x3600
	ds_read_b64_tr_b16 v[232:233], v250 offset:0x3e00
	s_waitcnt lgkmcnt(14)
	v_mfma_f32_32x32x16_bf16 v[18:33], v[130:133], v[202:205], v[18:33]
	s_waitcnt lgkmcnt(12)
	v_mfma_f32_32x32x16_bf16 v[18:33], v[126:129], v[206:209], v[18:33]
	s_waitcnt lgkmcnt(10)
	v_mfma_f32_32x32x16_bf16 v[18:33], v[122:125], v[210:213], v[18:33]
	s_waitcnt lgkmcnt(8)
	v_mfma_f32_32x32x16_bf16 v[18:33], v[118:121], v[214:217], v[18:33]
	s_waitcnt lgkmcnt(6)
	v_mfma_f32_32x32x16_bf16 v[2:17], v[130:133], v[218:221], v[2:17]
	s_waitcnt lgkmcnt(4)
	v_mfma_f32_32x32x16_bf16 v[2:17], v[126:129], v[222:225], v[2:17]
	s_waitcnt lgkmcnt(2)
	v_mfma_f32_32x32x16_bf16 v[2:17], v[122:125], v[226:229], v[2:17]
	s_waitcnt lgkmcnt(0)
	v_mfma_f32_32x32x16_bf16 v[2:17], v[118:121], v[230:233], v[2:17]
	s_and_b64 vcc, exec, s[6:7]
	s_cbranch_vccnz .LBB0_668
	s_waitcnt vmcnt(0)

.LBB0_678:
	s_barrier
	s_setprio 3
	ds_read_b128 v[66:69], v161
	ds_read_b128 v[70:73], v161 offset:8192
	ds_read_b128 v[204:207], v163
	ds_read_b128 v[208:211], v163 offset:8192
	ds_read_b128 v[212:215], v165
	ds_read_b128 v[216:219], v165 offset:8192
	ds_read_b128 v[220:223], v167
	ds_read_b128 v[224:227], v167 offset:8192
	v_add_u32_e32 v252, s12, v185
	s_waitcnt lgkmcnt(7)
	v_mfma_f32_32x32x16_bf16 v[82:97], v[66:69], v[114:117], 0
	s_waitcnt lgkmcnt(6)
	v_mfma_f32_32x32x16_bf16 v[66:81], v[70:73], v[114:117], 0
	s_waitcnt lgkmcnt(5)
	v_mfma_f32_32x32x16_bf16 v[82:97], v[204:207], v[110:113], v[82:97]
	s_waitcnt lgkmcnt(4)
	v_mfma_f32_32x32x16_bf16 v[66:81], v[208:211], v[110:113], v[66:81]
	ds_read_b128 v[204:207], v169 offset:8192
	ds_read_b128 v[208:211], v171
	ds_read_b128 v[228:231], v171 offset:8192
	ds_read_b128 v[232:235], v169
	ds_read_b128 v[236:239], v159
	s_waitcnt lgkmcnt(8)
	v_mfma_f32_32x32x16_bf16 v[82:97], v[212:215], v[106:109], v[82:97]
	s_waitcnt lgkmcnt(7)
	v_mfma_f32_32x32x16_bf16 v[66:81], v[216:219], v[106:109], v[66:81]
	s_waitcnt lgkmcnt(6)
	v_mfma_f32_32x32x16_bf16 v[82:97], v[220:223], v[102:105], v[82:97]
	s_waitcnt lgkmcnt(5)
	v_mfma_f32_32x32x16_bf16 v[66:81], v[224:227], v[102:105], v[66:81]
	ds_read_b128 v[212:215], v173
	ds_read_b128 v[216:219], v173 offset:8192
	ds_read_b128 v[220:223], v175
	ds_read_b128 v[224:227], v175 offset:8192
	ds_read_b128 v[240:243], v159 offset:1024
	ds_read_b128 v[244:247], v159 offset:2048
	s_waitcnt lgkmcnt(7)
	v_mfma_f32_32x32x16_bf16 v[82:97], v[232:235], v[98:101], v[82:97]
	v_mfma_f32_32x32x16_bf16 v[66:81], v[204:207], v[98:101], v[66:81]
	s_waitcnt lgkmcnt(6)
	v_mfma_f32_32x32x16_bf16 v[82:97], v[208:211], v[236:239], v[82:97]
	v_mfma_f32_32x32x16_bf16 v[66:81], v[228:231], v[236:239], v[66:81]
	ds_read_b128 v[204:207], v178 offset:32768
	ds_read_b128 v[208:211], v178 offset:36864
	ds_read_b128 v[228:231], v180 offset:32768
	ds_read_b128 v[232:235], v180 offset:36864
	ds_read_b128 v[236:239], v159 offset:3072
	ds_read_b128 v[248:251], v159 offset:4096
	s_waitcnt lgkmcnt(7)
	v_mfma_f32_32x32x16_bf16 v[82:97], v[212:215], v[240:243], v[82:97]
	v_mfma_f32_32x32x16_bf16 v[66:81], v[216:219], v[240:243], v[66:81]
	s_waitcnt lgkmcnt(6)
	v_mfma_f32_32x32x16_bf16 v[82:97], v[220:223], v[244:247], v[82:97]
	v_mfma_f32_32x32x16_bf16 v[66:81], v[224:227], v[244:247], v[66:81]
	ds_read_b128 v[212:215], v182 offset:32768
	ds_read_b128 v[216:219], v182 offset:36864
	ds_read_b128 v[220:223], v184 offset:32768
	ds_read_b128 v[224:227], v184 offset:36864
	ds_read_b128 v[240:243], v159 offset:5120
	ds_read_b128 v[244:247], v159 offset:6144
	s_waitcnt lgkmcnt(7)
	v_mfma_f32_32x32x16_bf16 v[82:97], v[204:207], v[236:239], v[82:97]
	v_mfma_f32_32x32x16_bf16 v[66:81], v[208:211], v[236:239], v[66:81]
	s_waitcnt lgkmcnt(6)
	v_mfma_f32_32x32x16_bf16 v[82:97], v[228:231], v[248:251], v[82:97]
	v_mfma_f32_32x32x16_bf16 v[66:81], v[232:235], v[248:251], v[66:81]
	s_waitcnt lgkmcnt(1)
	v_mfma_f32_32x32x16_bf16 v[82:97], v[212:215], v[240:243], v[82:97]
	v_mfma_f32_32x32x16_bf16 v[66:81], v[216:219], v[240:243], v[66:81]
	s_waitcnt lgkmcnt(0)
	v_mfma_f32_32x32x16_bf16 v[82:97], v[220:223], v[244:247], v[82:97]
	v_mfma_f32_32x32x16_bf16 v[66:81], v[224:227], v[244:247], v[66:81]
	ds_read_b64_tr_b16 v[204:205], v252 offset:0
	ds_read_b64_tr_b16 v[206:207], v252 offset:0x800
	ds_read_b64_tr_b16 v[208:209], v252 offset:0x1000
	ds_read_b64_tr_b16 v[210:211], v252 offset:0x1800
	ds_read_b64_tr_b16 v[212:213], v252 offset:0x2000
	ds_read_b64_tr_b16 v[214:215], v252 offset:0x2800
	ds_read_b64_tr_b16 v[216:217], v252 offset:0x3000
	ds_read_b64_tr_b16 v[218:219], v252 offset:0x3800
	ds_read_b64_tr_b16 v[220:221], v252 offset:0x200
	ds_read_b64_tr_b16 v[222:223], v252 offset:0xa00
	ds_read_b64_tr_b16 v[224:225], v252 offset:0x1200
	ds_read_b64_tr_b16 v[226:227], v252 offset:0x1a00
	ds_read_b64_tr_b16 v[228:229], v252 offset:0x2200
	ds_read_b64_tr_b16 v[230:231], v252 offset:0x2a00
	ds_read_b64_tr_b16 v[232:233], v252 offset:0x3200
	ds_read_b64_tr_b16 v[234:235], v252 offset:0x3a00
	s_nop 0
	s_waitcnt lgkmcnt(14)
	v_mfma_f32_32x32x16_bf16 v[50:65], v[130:133], v[204:207], v[50:65]
	s_waitcnt lgkmcnt(12)
	v_mfma_f32_32x32x16_bf16 v[50:65], v[126:129], v[208:211], v[50:65]
	s_waitcnt lgkmcnt(10)
	v_mfma_f32_32x32x16_bf16 v[50:65], v[122:125], v[212:215], v[50:65]
	s_waitcnt lgkmcnt(8)
	v_mfma_f32_32x32x16_bf16 v[50:65], v[118:121], v[216:219], v[50:65]
	ds_read_b64_tr_b16 v[204:205], v252 offset:0x400
	ds_read_b64_tr_b16 v[206:207], v252 offset:0xc00
	ds_read_b64_tr_b16 v[208:209], v252 offset:0x1400
	ds_read_b64_tr_b16 v[210:211], v252 offset:0x1c00
	ds_read_b64_tr_b16 v[212:213], v252 offset:0x2400
	ds_read_b64_tr_b16 v[214:215], v252 offset:0x2c00
	ds_read_b64_tr_b16 v[216:217], v252 offset:0x3400
	ds_read_b64_tr_b16 v[218:219], v252 offset:0x3c00
	s_waitcnt lgkmcnt(14)
	v_mfma_f32_32x32x16_bf16 v[34:49], v[130:133], v[220:223], v[34:49]
	s_waitcnt lgkmcnt(12)
	v_mfma_f32_32x32x16_bf16 v[34:49], v[126:129], v[224:227], v[34:49]
	s_waitcnt lgkmcnt(10)
	v_mfma_f32_32x32x16_bf16 v[34:49], v[122:125], v[228:231], v[34:49]
	s_waitcnt lgkmcnt(8)
	v_mfma_f32_32x32x16_bf16 v[34:49], v[118:121], v[232:235], v[34:49]
	ds_read_b64_tr_b16 v[220:221], v252 offset:0x600
	ds_read_b64_tr_b16 v[222:223], v252 offset:0xe00
	ds_read_b64_tr_b16 v[224:225], v252 offset:0x1600
	ds_read_b64_tr_b16 v[226:227], v252 offset:0x1e00
	ds_read_b64_tr_b16 v[228:229], v252 offset:0x2600
	ds_read_b64_tr_b16 v[230:231], v252 offset:0x2e00
	ds_read_b64_tr_b16 v[232:233], v252 offset:0x3600
	ds_read_b64_tr_b16 v[234:235], v252 offset:0x3e00
	s_waitcnt lgkmcnt(14)
	v_mfma_f32_32x32x16_bf16 v[18:33], v[130:133], v[204:207], v[18:33]
	s_waitcnt lgkmcnt(12)
	v_mfma_f32_32x32x16_bf16 v[18:33], v[126:129], v[208:211], v[18:33]
	s_waitcnt lgkmcnt(10)
	v_mfma_f32_32x32x16_bf16 v[18:33], v[122:125], v[212:215], v[18:33]
	s_waitcnt lgkmcnt(8)
	v_mfma_f32_32x32x16_bf16 v[18:33], v[118:121], v[216:219], v[18:33]
	s_waitcnt lgkmcnt(6)
	v_mfma_f32_32x32x16_bf16 v[2:17], v[130:133], v[220:223], v[2:17]
	s_waitcnt lgkmcnt(4)
	v_mfma_f32_32x32x16_bf16 v[2:17], v[126:129], v[224:227], v[2:17]
	s_waitcnt lgkmcnt(2)
	v_mfma_f32_32x32x16_bf16 v[2:17], v[122:125], v[228:231], v[2:17]
	s_waitcnt lgkmcnt(0)
	v_mfma_f32_32x32x16_bf16 v[2:17], v[118:121], v[232:235], v[2:17]
	s_and_b64 vcc, exec, s[6:7]
	s_cbranch_vccnz .LBB0_680
	s_waitcnt vmcnt(0)
